# hyconv dl loop: per-wave active range (39 of 63 iterations), scalar block guards, LDS fragment reads prefetched one iteration ahead
# speedup vs baseline: 1.0458x; 1.0176x over previous
; __device__ __forceinline__ void phase_hyconv(CP& p, char* smem) {
;     ...
; #pragma unroll
;     for (int s = 1; s < 4; ++s)
; #pragma unroll
;       for (int i = 0; i < 2; ++i) {
;         const int ch = tid + 256 * i;
;         unsigned e[8];
; #pragma unroll
;         for (int j = 0; j < 8; ++j) { const int idx = 8 * ch + s + j; e[j] = idx < 4096 ? (unsigned)cp[idx] : 0u; }
;         uint4 u; u.x = e[0] | (e[1] << 16); u.y = e[2] | (e[3] << 16); u.z = e[4] | (e[5] << 16); u.w = e[6] | (e[7] << 16);
;         *(uint4*)(cp + s * 4128 + 8 * ch) = u;
;       }
;     __syncthreads();
;     const bf16_t* abase = cp + si * 4128 + (2048 - i16 - si + 8 * g4);
;     f32x4 acc[4][4];
; #pragma unroll
;     for (int m = 0; m < 4; ++m)
; #pragma unroll
;       for (int n = 0; n < 4; ++n) acc[m][n] = (f32x4){0.f, 0.f, 0.f, 0.f};
;     for (int dl = -31; dl <= 31; ++dl) {
;       bf16x8 af[4][2];
; #pragma unroll
;       for (int mt = 0; mt < 4; ++mt)
; #pragma unroll
;         for (int kk = 0; kk < 2; ++kk) {
;           const bf16_t* ap = abase - 64 * dl - 16 * mt + 32 * kk;
;           const uint2 lo = *(const uint2*)ap, hi = *(const uint2*)(ap + 4);
;           union { uint4 u; bf16x8 v; } cv; cv.u.x = lo.x; cv.u.y = lo.y; cv.u.z = hi.x; cv.u.w = hi.y;
;           af[mt][kk] = cv.v;
;         }
; #pragma unroll
;       for (int jt = 0; jt < 4; ++jt) {
;         const int in0 = ocb + 16 * jt - 8 * dl;
;         if (in0 >= -8 && in0 <= 248) {
;           const bf16_t* bp = Vl + (in0 + 8 + i16) * 80 + 8 * g4;
;           const bf16x8 b0 = *(const bf16x8*)bp, b1 = *(const bf16x8*)(bp + 32);
; #pragma unroll
;           for (int mt = 0; mt < 4; ++mt) {
;             acc[mt][jt] = __builtin_amdgcn_mfma_f32_16x16x32_bf16(af[mt][0], b0, acc[mt][jt], 0, 0, 0);
;             acc[mt][jt] = __builtin_amdgcn_mfma_f32_16x16x32_bf16(af[mt][1], b1, acc[mt][jt], 0, 0, 0);
;           }
;         }
;       }
;     }
.LBB0_2951:
	s_or_b64 exec, exec, s[46:47]
	s_waitcnt lgkmcnt(0)
	v_or_b32_e32 v17, v10, v5
	v_or_b32_e32 v16, v4, v3
	v_or_b32_e32 v19, v14, v13
	v_or_b32_e32 v18, v12, v11
	v_mov_b32_e32 v4, v2
	v_mov_b32_e32 v5, v2
	ds_write_b128 v130, v[16:19] offset:28864
	v_mov_b32_e32 v3, v2
	v_mov_b64_e32 v[44:45], v[4:5]
	v_mov_b64_e32 v[48:49], v[4:5]
	v_mov_b64_e32 v[52:53], v[4:5]
	v_mov_b64_e32 v[56:57], v[4:5]
	v_mov_b64_e32 v[60:61], v[4:5]
	v_mov_b64_e32 v[64:65], v[4:5]
	v_mov_b64_e32 v[68:69], v[4:5]
	v_mov_b64_e32 v[72:73], v[4:5]
	v_mov_b64_e32 v[40:41], v[4:5]
	v_mov_b64_e32 v[36:37], v[4:5]
	v_mov_b64_e32 v[32:33], v[4:5]
	v_mov_b64_e32 v[28:29], v[4:5]
	v_mov_b64_e32 v[24:25], v[4:5]
	v_mov_b64_e32 v[20:21], v[4:5]
	v_mov_b64_e32 v[16:17], v[4:5]
	v_mov_b64_e32 v[12:13], v[4:5]
	v_mov_b32_e32 v140, v133
	v_mov_b32_e32 v141, v113
	v_mov_b64_e32 v[42:43], v[2:3]
	v_mov_b64_e32 v[46:47], v[2:3]
	v_mov_b64_e32 v[50:51], v[2:3]
	v_mov_b64_e32 v[54:55], v[2:3]
	v_mov_b64_e32 v[58:59], v[2:3]
	v_mov_b64_e32 v[62:63], v[2:3]
	v_mov_b64_e32 v[66:67], v[2:3]
	v_mov_b64_e32 v[70:71], v[2:3]
	v_mov_b64_e32 v[38:39], v[2:3]
	v_mov_b64_e32 v[34:35], v[2:3]
	v_mov_b64_e32 v[30:31], v[2:3]
	v_mov_b64_e32 v[26:27], v[2:3]
	v_mov_b64_e32 v[22:23], v[2:3]
	v_mov_b64_e32 v[18:19], v[2:3]
	v_mov_b64_e32 v[14:15], v[2:3]
	v_mov_b64_e32 v[10:11], v[2:3]
	s_waitcnt lgkmcnt(0)
	s_barrier
	v_readfirstlane_b32 s46, v124
	s_lshl_b32 s47, s46, 4
	s_mul_i32 s46, s46, 0xa0
	v_add_u32_e32 v234, v113, v128
	v_add_u32_e32 v235, v133, v128
	v_subrev_u32_e32 v234, s47, v234
	v_add_u32_e32 v235, 0x12100, v235
	v_subrev_u32_e32 v235, s46, v235
	s_mov_b32 s51, 0
	ds_read2_b64 v[74:77], v234 offset0:12 offset1:13
	ds_read2_b64 v[78:81], v234 offset0:8 offset1:9
	ds_read2_b64 v[94:97], v234 offset0:20 offset1:21
	ds_read2_b64 v[86:89], v234 offset0:16 offset1:17
	ds_read2_b64 v[90:93], v234 offset0:4 offset1:5
	ds_read2_b64 v[82:85], v234 offset1:1
	ds_read_b128 v[142:145], v235
	ds_read_b128 v[146:149], v235 offset:64
.Lhy_body_X:
	s_waitcnt lgkmcnt(0)
	s_cmp_ge_u32 s51, 38
	s_cbranch_scc1 .Lhy_X_m0
	v_add_u32_e32 v234, 0xffffff80, v234
	v_add_u32_e32 v235, 0xfffffb00, v235
	ds_read2_b64 v[178:181], v234 offset0:12 offset1:13
	ds_read2_b64 v[182:185], v234 offset0:8 offset1:9
	ds_read2_b64 v[198:201], v234 offset0:20 offset1:21
	ds_read2_b64 v[190:193], v234 offset0:16 offset1:17
	ds_read2_b64 v[194:197], v234 offset0:4 offset1:5
	ds_read2_b64 v[186:189], v234 offset1:1
	s_cmp_gt_u32 s51, 31
	s_cbranch_scc1 .Lhy_X_r1
	ds_read_b128 v[202:205], v235
	ds_read_b128 v[206:209], v235 offset:64
.Lhy_X_r1:
	s_sub_u32 s46, s51, 1
	s_cmp_gt_u32 s46, 32
	s_cbranch_scc1 .Lhy_X_r2
	ds_read_b128 v[210:213], v235 offset:2560
	ds_read_b128 v[214:217], v235 offset:2624
.Lhy_X_r2:
	s_sub_u32 s46, s51, 3
	s_cmp_gt_u32 s46, 32
	s_cbranch_scc1 .Lhy_X_r3
	ds_read_b128 v[218:221], v235 offset:5120
	ds_read_b128 v[222:225], v235 offset:5184
.Lhy_X_r3:
	s_sub_u32 s46, s51, 5
	s_cmp_gt_u32 s46, 32
	s_cbranch_scc1 .Lhy_X_m0
	ds_read_b128 v[226:229], v235 offset:7680
	ds_read_b128 v[230:233], v235 offset:7744
.Lhy_X_m0:
	s_cmp_gt_u32 s51, 32
	s_cbranch_scc1 .Lhy_X_m1
	v_mfma_f32_16x16x32_bf16 v[70:73], v[74:77], v[142:145], v[70:73]
	v_mfma_f32_16x16x32_bf16 v[54:57], v[78:81], v[142:145], v[54:57]
	v_mfma_f32_16x16x32_bf16 v[38:41], v[90:93], v[142:145], v[38:41]
	v_mfma_f32_16x16x32_bf16 v[22:25], v[82:85], v[142:145], v[22:25]
	v_mfma_f32_16x16x32_bf16 v[70:73], v[94:97], v[146:149], v[70:73]
	v_mfma_f32_16x16x32_bf16 v[54:57], v[86:89], v[146:149], v[54:57]
	v_mfma_f32_16x16x32_bf16 v[38:41], v[74:77], v[146:149], v[38:41]
	v_mfma_f32_16x16x32_bf16 v[22:25], v[78:81], v[146:149], v[22:25]
.Lhy_X_m1:
	s_sub_u32 s46, s51, 2
	s_cmp_gt_u32 s46, 32
	s_cbranch_scc1 .Lhy_X_m2
	v_mfma_f32_16x16x32_bf16 v[66:69], v[74:77], v[154:157], v[66:69]
	v_mfma_f32_16x16x32_bf16 v[50:53], v[78:81], v[154:157], v[50:53]
	v_mfma_f32_16x16x32_bf16 v[34:37], v[90:93], v[154:157], v[34:37]
	v_mfma_f32_16x16x32_bf16 v[18:21], v[82:85], v[154:157], v[18:21]
	v_mfma_f32_16x16x32_bf16 v[66:69], v[94:97], v[158:161], v[66:69]
	v_mfma_f32_16x16x32_bf16 v[50:53], v[86:89], v[158:161], v[50:53]
	v_mfma_f32_16x16x32_bf16 v[34:37], v[74:77], v[158:161], v[34:37]
	v_mfma_f32_16x16x32_bf16 v[18:21], v[78:81], v[158:161], v[18:21]
.Lhy_X_m2:
	s_sub_u32 s46, s51, 4
	s_cmp_gt_u32 s46, 32
	s_cbranch_scc1 .Lhy_X_m3
	v_mfma_f32_16x16x32_bf16 v[62:65], v[74:77], v[162:165], v[62:65]
	v_mfma_f32_16x16x32_bf16 v[46:49], v[78:81], v[162:165], v[46:49]
	v_mfma_f32_16x16x32_bf16 v[30:33], v[90:93], v[162:165], v[30:33]
	v_mfma_f32_16x16x32_bf16 v[14:17], v[82:85], v[162:165], v[14:17]
	v_mfma_f32_16x16x32_bf16 v[62:65], v[94:97], v[166:169], v[62:65]
	v_mfma_f32_16x16x32_bf16 v[46:49], v[86:89], v[166:169], v[46:49]
	v_mfma_f32_16x16x32_bf16 v[30:33], v[74:77], v[166:169], v[30:33]
	v_mfma_f32_16x16x32_bf16 v[14:17], v[78:81], v[166:169], v[14:17]
; __device__ __forceinline__ void xcd_barrier(const XcdBarrier& b) {
;     asm volatile("s_waitcnt vmcnt(0)" ::: "memory");
;     __syncthreads();
;     if (threadIdx.x == 0) {
;         unsigned* bar = b.bar;
;         __builtin_amdgcn_s_waitcnt(0);
;         unsigned nloc = b.st[0], nx = b.st[1];
;         if (nloc == 0u) { xcd_barrier_complete(bar, b.x, nloc, nx); b.st[0] = nloc; b.st[1] = nx; }
; __device__ __forceinline__ void phase_hyconv(CP& p, char* smem) {
;     ...
;     for (int dl = -31; dl <= 31; ++dl) {
;       bf16x8 af[4][2];
; #pragma unroll
;       for (int mt = 0; mt < 4; ++mt)
; #pragma unroll
;         for (int kk = 0; kk < 2; ++kk) {
;           const bf16_t* ap = abase - 64 * dl - 16 * mt + 32 * kk;
;           const uint2 lo = *(const uint2*)ap, hi = *(const uint2*)(ap + 4);
;           union { uint4 u; bf16x8 v; } cv; cv.u.x = lo.x; cv.u.y = lo.y; cv.u.z = hi.x; cv.u.w = hi.y;
;           af[mt][kk] = cv.v;
;         }
; #pragma unroll
;       for (int jt = 0; jt < 4; ++jt) {
;         const int in0 = ocb + 16 * jt - 8 * dl;
;         if (in0 >= -8 && in0 <= 248) {
;           const bf16_t* bp = Vl + (in0 + 8 + i16) * 80 + 8 * g4;
;           const bf16x8 b0 = *(const bf16x8*)bp, b1 = *(const bf16x8*)(bp + 32);
; #pragma unroll
;           for (int mt = 0; mt < 4; ++mt) {
;             acc[mt][jt] = __builtin_amdgcn_mfma_f32_16x16x32_bf16(af[mt][0], b0, acc[mt][jt], 0, 0, 0);
;             acc[mt][jt] = __builtin_amdgcn_mfma_f32_16x16x32_bf16(af[mt][1], b1, acc[mt][jt], 0, 0, 0);
;           }
;         }
;       }
;     }
.Lhy_X_m3:
	s_sub_u32 s46, s51, 6
	s_cmp_gt_u32 s46, 32
	s_cbranch_scc1 .Lhy_X_end
	v_mfma_f32_16x16x32_bf16 v[58:61], v[74:77], v[170:173], v[58:61]
	v_mfma_f32_16x16x32_bf16 v[42:45], v[78:81], v[170:173], v[42:45]
	v_mfma_f32_16x16x32_bf16 v[26:29], v[90:93], v[170:173], v[26:29]
	v_mfma_f32_16x16x32_bf16 v[10:13], v[82:85], v[170:173], v[10:13]
	v_mfma_f32_16x16x32_bf16 v[58:61], v[94:97], v[174:177], v[58:61]
	v_mfma_f32_16x16x32_bf16 v[42:45], v[86:89], v[174:177], v[42:45]
	v_mfma_f32_16x16x32_bf16 v[26:29], v[74:77], v[174:177], v[26:29]
	v_mfma_f32_16x16x32_bf16 v[10:13], v[78:81], v[174:177], v[10:13]
.Lhy_X_end:
	s_add_u32 s51, s51, 1
	s_cmp_eq_u32 s51, 39
	s_cbranch_scc1 .Lhy_done
.Lhy_body_Y:
	s_waitcnt lgkmcnt(0)
	s_cmp_ge_u32 s51, 38
	s_cbranch_scc1 .Lhy_Y_m0
	v_add_u32_e32 v234, 0xffffff80, v234
	v_add_u32_e32 v235, 0xfffffb00, v235
	ds_read2_b64 v[74:77], v234 offset0:12 offset1:13
	ds_read2_b64 v[78:81], v234 offset0:8 offset1:9
	ds_read2_b64 v[94:97], v234 offset0:20 offset1:21
	ds_read2_b64 v[86:89], v234 offset0:16 offset1:17
	ds_read2_b64 v[90:93], v234 offset0:4 offset1:5
	ds_read2_b64 v[82:85], v234 offset1:1
	s_cmp_gt_u32 s51, 31
	s_cbranch_scc1 .Lhy_Y_r1
	ds_read_b128 v[142:145], v235
	ds_read_b128 v[146:149], v235 offset:64
.Lhy_Y_r1:
	s_sub_u32 s46, s51, 1
	s_cmp_gt_u32 s46, 32
	s_cbranch_scc1 .Lhy_Y_r2
	ds_read_b128 v[154:157], v235 offset:2560
	ds_read_b128 v[158:161], v235 offset:2624
.Lhy_Y_r2:
	s_sub_u32 s46, s51, 3
	s_cmp_gt_u32 s46, 32
	s_cbranch_scc1 .Lhy_Y_r3
	ds_read_b128 v[162:165], v235 offset:5120
	ds_read_b128 v[166:169], v235 offset:5184
.Lhy_Y_r3:
	s_sub_u32 s46, s51, 5
	s_cmp_gt_u32 s46, 32
	s_cbranch_scc1 .Lhy_Y_m0
	ds_read_b128 v[170:173], v235 offset:7680
	ds_read_b128 v[174:177], v235 offset:7744
.Lhy_Y_m0:
	s_cmp_gt_u32 s51, 32
	s_cbranch_scc1 .Lhy_Y_m1
	v_mfma_f32_16x16x32_bf16 v[70:73], v[178:181], v[202:205], v[70:73]
	v_mfma_f32_16x16x32_bf16 v[54:57], v[182:185], v[202:205], v[54:57]
	v_mfma_f32_16x16x32_bf16 v[38:41], v[194:197], v[202:205], v[38:41]
	v_mfma_f32_16x16x32_bf16 v[22:25], v[186:189], v[202:205], v[22:25]
	v_mfma_f32_16x16x32_bf16 v[70:73], v[198:201], v[206:209], v[70:73]
	v_mfma_f32_16x16x32_bf16 v[54:57], v[190:193], v[206:209], v[54:57]
	v_mfma_f32_16x16x32_bf16 v[38:41], v[178:181], v[206:209], v[38:41]
	v_mfma_f32_16x16x32_bf16 v[22:25], v[182:185], v[206:209], v[22:25]
.Lhy_Y_m1:
	s_sub_u32 s46, s51, 2
	s_cmp_gt_u32 s46, 32
	s_cbranch_scc1 .Lhy_Y_m2
	v_mfma_f32_16x16x32_bf16 v[66:69], v[178:181], v[210:213], v[66:69]
	v_mfma_f32_16x16x32_bf16 v[50:53], v[182:185], v[210:213], v[50:53]
	v_mfma_f32_16x16x32_bf16 v[34:37], v[194:197], v[210:213], v[34:37]
	v_mfma_f32_16x16x32_bf16 v[18:21], v[186:189], v[210:213], v[18:21]
	v_mfma_f32_16x16x32_bf16 v[66:69], v[198:201], v[214:217], v[66:69]
	v_mfma_f32_16x16x32_bf16 v[50:53], v[190:193], v[214:217], v[50:53]
	v_mfma_f32_16x16x32_bf16 v[34:37], v[178:181], v[214:217], v[34:37]
	v_mfma_f32_16x16x32_bf16 v[18:21], v[182:185], v[214:217], v[18:21]
.Lhy_Y_m2:
	s_sub_u32 s46, s51, 4
	s_cmp_gt_u32 s46, 32
	s_cbranch_scc1 .Lhy_Y_m3
	v_mfma_f32_16x16x32_bf16 v[62:65], v[178:181], v[218:221], v[62:65]
	v_mfma_f32_16x16x32_bf16 v[46:49], v[182:185], v[218:221], v[46:49]
	v_mfma_f32_16x16x32_bf16 v[30:33], v[194:197], v[218:221], v[30:33]
	v_mfma_f32_16x16x32_bf16 v[14:17], v[186:189], v[218:221], v[14:17]
	v_mfma_f32_16x16x32_bf16 v[62:65], v[198:201], v[222:225], v[62:65]
	v_mfma_f32_16x16x32_bf16 v[46:49], v[190:193], v[222:225], v[46:49]
	v_mfma_f32_16x16x32_bf16 v[30:33], v[178:181], v[222:225], v[30:33]
	v_mfma_f32_16x16x32_bf16 v[14:17], v[182:185], v[222:225], v[14:17]
.Lhy_Y_m3:
	s_sub_u32 s46, s51, 6
	s_cmp_gt_u32 s46, 32
	s_cbranch_scc1 .Lhy_Y_end
	v_mfma_f32_16x16x32_bf16 v[58:61], v[178:181], v[226:229], v[58:61]
	v_mfma_f32_16x16x32_bf16 v[42:45], v[182:185], v[226:229], v[42:45]
	v_mfma_f32_16x16x32_bf16 v[26:29], v[194:197], v[226:229], v[26:29]
	v_mfma_f32_16x16x32_bf16 v[10:13], v[186:189], v[226:229], v[10:13]
	v_mfma_f32_16x16x32_bf16 v[58:61], v[198:201], v[230:233], v[58:61]
	v_mfma_f32_16x16x32_bf16 v[42:45], v[190:193], v[230:233], v[42:45]
	v_mfma_f32_16x16x32_bf16 v[26:29], v[178:181], v[230:233], v[26:29]
	v_mfma_f32_16x16x32_bf16 v[10:13], v[182:185], v[230:233], v[10:13]
.Lhy_Y_end:
	s_add_u32 s51, s51, 1
	s_cmp_eq_u32 s51, 39
	s_cbranch_scc1 .Lhy_done
	s_branch .Lhy_body_X
.Lhy_done:
	s_branch .LBB0_2850
.LBB0_2961:
	s_cmp_lt_i32 s53, 14
	s_cbranch_scc1 .LBB0_3029
	s_cmpk_lt_u32 s53, 0x3e9
	s_mov_b64 s[4:5], -1
	s_cbranch_scc0 .LBB0_3016
	s_waitcnt vmcnt(0)
	s_waitcnt lgkmcnt(0)
	s_barrier
	s_and_saveexec_b64 s[4:5], s[86:87]
	s_cbranch_execz .LBB0_3015
	v_mov_b32_e32 v2, 0x27ff0
	s_waitcnt vmcnt(0) expcnt(0) lgkmcnt(0)
	ds_read_b32 v4, v2
	v_mov_b32_e32 v2, 0x27ff4
	ds_read_b32 v2, v2
	s_waitcnt lgkmcnt(1)
	v_cmp_ne_u32_e32 vcc, 0, v4
	s_cbranch_vccnz .LBB0_2979
	s_add_u32 s6, s66, 0x1000
	s_addc_u32 s7, s67, 0
	s_add_u32 s8, s66, 0x1100
	s_addc_u32 s9, s67, 0
	s_add_u32 s10, s66, 0x1200
	s_addc_u32 s11, s67, 0
	s_mul_i32 s3, s55, s84
	s_add_u32 s12, s66, 0x1300
	s_mul_i32 s3, s3, s54
	s_addc_u32 s13, s67, 0
	s_mov_b32 s20, 1
	v_mov_b32_e32 v18, 0
	s_branch .LBB0_2967
